# FFN1-in phase idle-slot work: K/V cache f32->bf16 copy issues all of a thread's loads up front (one round trip, pointers read once) instead of five dependent iterations
# baseline (speedup 1.0000x reference)
; __device__ __forceinline__ unsigned pk2(float lo, float hi) { return pg8::cvt_pk_bf16(lo, hi); }
; #define AIN(i) arg_in(i)
; __global__ void __launch_bounds__(NTHREADS, 2) fwd_megakernel(Args a) {
;     ...
;             const size_t nvec = (size_t)8 * 512 * 1024 / 8;
;             for (size_t v = (size_t)ib * NTHREADS + tid; v < nvec; v += (size_t)nib * NTHREADS) {
;                 const f32x4 k0 = *(const f32x4*)(AIN(2) + v * 8), k1 = *(const f32x4*)(AIN(2) + v * 8 + 4), v0 = *(const f32x4*)(AIN(3) + v * 8), v1 = *(const f32x4*)(AIN(3) + v * 8 + 4);
;                 *(u32x4*)(CKB + v * 8) = (u32x4){pk2(k0[0], k0[1]), pk2(k0[2], k0[3]), pk2(k1[0], k1[1]), pk2(k1[2], k1[3])};
;                 *(u32x4*)(CVB + v * 8) = (u32x4){pk2(v0[0], v0[1]), pk2(v0[2], v0[3]), pk2(v1[0], v1[1]), pk2(v1[2], v1[3])};
;             }
.LBB0_185:
	s_mov_b32 s17, 0
	s_lshl_b64 s[2:3], s[16:17], 9
	v_ashrrev_i32_e32 v15, 31, v14
	v_lshl_add_u64 v[2:3], s[2:3], 0, v[14:15]
	s_mov_b64 s[2:3], 0x80000
	v_cmp_gt_u64_e32 vcc, s[2:3], v[2:3]
	s_and_saveexec_b64 s[6:7], vcc
	s_cbranch_execz .LBB0_188
	s_ashr_i32 s19, s18, 31
	s_lshl_b64 s[2:3], s[16:17], 14
	v_lshlrev_b64 v[4:5], 5, v[14:15]
	s_ashr_i32 s15, s14, 31
	s_lshl_b64 s[8:9], s[18:19], 9
	v_lshl_add_u64 v[4:5], s[2:3], 0, v[4:5]
	s_lshl_b64 s[2:3], s[74:75], 14
	s_lshl_b64 s[10:11], s[14:15], 14
	s_sub_u32 s10, s2, s10
	s_subb_u32 s11, s3, s11
	s_lshl_b64 s[2:3], s[16:17], 13
	s_load_dwordx4 s[16:19], s[90:91], 0xa8
	s_add_u32 s1, s4, s2
	s_addc_u32 s3, s5, s3
	s_waitcnt lgkmcnt(0)
	s_mov_b64 s[16:17], 0x7ffff
	s_add_u32 s2, s18, s1
	s_addc_u32 s3, s19, s3
	v_lshl_add_u64 v[6:7], v[14:15], 4, s[2:3]
	s_mov_b64 s[2:3], 0x3780000
	v_lshl_add_u64 v[6:7], v[6:7], 0, s[2:3]
	s_lshl_b64 s[2:3], s[74:75], 13
	s_lshl_b64 s[4:5], s[14:15], 13
	s_sub_u32 s4, s2, s4
	s_subb_u32 s5, s3, s5
	s_mov_b64 s[14:15], 0
	s_load_dwordx4 s[20:23], s[90:91], 0x10
	s_mov_b64 s[24:25], exec
	s_waitcnt lgkmcnt(0)
	v_lshl_add_u64 v[26:27], s[20:21], 0, v[4:5]
	v_lshl_add_u64 v[28:29], s[22:23], 0, v[4:5]
	global_load_dwordx4 v[32:35], v[26:27], off
	global_load_dwordx4 v[36:39], v[26:27], off offset:16
	global_load_dwordx4 v[40:43], v[28:29], off
	global_load_dwordx4 v[44:47], v[28:29], off offset:16
	v_lshl_add_u64 v[2:3], v[2:3], 0, s[8:9]
	v_lshl_add_u64 v[26:27], v[26:27], 0, s[10:11]
	v_lshl_add_u64 v[28:29], v[28:29], 0, s[10:11]
	v_cmp_ge_u64_e32 vcc, s[16:17], v[2:3]
	s_and_b64 exec, exec, vcc
	s_mov_b64 s[26:27], exec
	global_load_dwordx4 v[48:51], v[26:27], off
	global_load_dwordx4 v[52:55], v[26:27], off offset:16
	global_load_dwordx4 v[56:59], v[28:29], off
	global_load_dwordx4 v[60:63], v[28:29], off offset:16
	v_lshl_add_u64 v[2:3], v[2:3], 0, s[8:9]
	v_lshl_add_u64 v[26:27], v[26:27], 0, s[10:11]
	v_lshl_add_u64 v[28:29], v[28:29], 0, s[10:11]
	v_cmp_ge_u64_e32 vcc, s[16:17], v[2:3]
	s_and_b64 exec, exec, vcc
	s_mov_b64 s[28:29], exec
	global_load_dwordx4 v[64:67], v[26:27], off
	global_load_dwordx4 v[68:71], v[26:27], off offset:16
	global_load_dwordx4 v[72:75], v[28:29], off
	global_load_dwordx4 v[76:79], v[28:29], off offset:16
	v_lshl_add_u64 v[2:3], v[2:3], 0, s[8:9]
	v_lshl_add_u64 v[26:27], v[26:27], 0, s[10:11]
	v_lshl_add_u64 v[28:29], v[28:29], 0, s[10:11]
	v_cmp_ge_u64_e32 vcc, s[16:17], v[2:3]
	s_and_b64 exec, exec, vcc
	s_mov_b64 s[30:31], exec
	global_load_dwordx4 v[80:83], v[26:27], off
	global_load_dwordx4 v[84:87], v[26:27], off offset:16
	global_load_dwordx4 v[88:91], v[28:29], off
	global_load_dwordx4 v[92:95], v[28:29], off offset:16
	v_lshl_add_u64 v[2:3], v[2:3], 0, s[8:9]
	v_lshl_add_u64 v[26:27], v[26:27], 0, s[10:11]
	v_lshl_add_u64 v[28:29], v[28:29], 0, s[10:11]
	v_cmp_ge_u64_e32 vcc, s[16:17], v[2:3]
	s_and_b64 exec, exec, vcc
	s_mov_b64 s[34:35], exec
	global_load_dwordx4 v[96:99], v[26:27], off
	global_load_dwordx4 v[100:103], v[26:27], off offset:16
	global_load_dwordx4 v[104:107], v[28:29], off
	global_load_dwordx4 v[108:111], v[28:29], off offset:16
	s_mov_b64 s[20:21], 0x800000
	s_waitcnt vmcnt(0)
	s_mov_b64 exec, s[24:25]
	v_cvt_pk_bf16_f32 v32, v32, v33
	v_cvt_pk_bf16_f32 v33, v34, v35
	v_cvt_pk_bf16_f32 v34, v36, v37
	v_cvt_pk_bf16_f32 v35, v38, v39
	v_cvt_pk_bf16_f32 v40, v40, v41
	v_cvt_pk_bf16_f32 v41, v42, v43
	v_cvt_pk_bf16_f32 v42, v44, v45
	v_cvt_pk_bf16_f32 v43, v46, v47
	v_lshl_add_u64 v[24:25], v[6:7], 0, s[20:21]
	global_store_dwordx4 v[6:7], v[32:35], off
	global_store_dwordx4 v[24:25], v[40:43], off
	v_lshl_add_u64 v[6:7], v[6:7], 0, s[4:5]
	s_mov_b64 exec, s[26:27]
	v_cvt_pk_bf16_f32 v48, v48, v49
	v_cvt_pk_bf16_f32 v49, v50, v51
	v_cvt_pk_bf16_f32 v50, v52, v53
	v_cvt_pk_bf16_f32 v51, v54, v55
	v_cvt_pk_bf16_f32 v56, v56, v57
	v_cvt_pk_bf16_f32 v57, v58, v59
	v_cvt_pk_bf16_f32 v58, v60, v61
	v_cvt_pk_bf16_f32 v59, v62, v63
	v_lshl_add_u64 v[24:25], v[6:7], 0, s[20:21]
	global_store_dwordx4 v[6:7], v[48:51], off
	global_store_dwordx4 v[24:25], v[56:59], off
	v_lshl_add_u64 v[6:7], v[6:7], 0, s[4:5]
	s_mov_b64 exec, s[28:29]
	v_cvt_pk_bf16_f32 v64, v64, v65
	v_cvt_pk_bf16_f32 v65, v66, v67
	v_cvt_pk_bf16_f32 v66, v68, v69
	v_cvt_pk_bf16_f32 v67, v70, v71
	v_cvt_pk_bf16_f32 v72, v72, v73
	v_cvt_pk_bf16_f32 v73, v74, v75
	v_cvt_pk_bf16_f32 v74, v76, v77
	v_cvt_pk_bf16_f32 v75, v78, v79
	v_lshl_add_u64 v[24:25], v[6:7], 0, s[20:21]
	global_store_dwordx4 v[6:7], v[64:67], off
	global_store_dwordx4 v[24:25], v[72:75], off
	v_lshl_add_u64 v[6:7], v[6:7], 0, s[4:5]
	s_mov_b64 exec, s[30:31]
	v_cvt_pk_bf16_f32 v80, v80, v81
	v_cvt_pk_bf16_f32 v81, v82, v83
	v_cvt_pk_bf16_f32 v82, v84, v85
	v_cvt_pk_bf16_f32 v83, v86, v87
	v_cvt_pk_bf16_f32 v88, v88, v89
	v_cvt_pk_bf16_f32 v89, v90, v91
	v_cvt_pk_bf16_f32 v90, v92, v93
	v_cvt_pk_bf16_f32 v91, v94, v95
	v_lshl_add_u64 v[24:25], v[6:7], 0, s[20:21]
	global_store_dwordx4 v[6:7], v[80:83], off
	global_store_dwordx4 v[24:25], v[88:91], off
	v_lshl_add_u64 v[6:7], v[6:7], 0, s[4:5]
	s_mov_b64 exec, s[34:35]
	v_cvt_pk_bf16_f32 v96, v96, v97
	v_cvt_pk_bf16_f32 v97, v98, v99
	v_cvt_pk_bf16_f32 v98, v100, v101
	v_cvt_pk_bf16_f32 v99, v102, v103
	v_cvt_pk_bf16_f32 v104, v104, v105
	v_cvt_pk_bf16_f32 v105, v106, v107
	v_cvt_pk_bf16_f32 v106, v108, v109
	v_cvt_pk_bf16_f32 v107, v110, v111
	v_lshl_add_u64 v[24:25], v[6:7], 0, s[20:21]
	global_store_dwordx4 v[6:7], v[96:99], off
	global_store_dwordx4 v[24:25], v[104:107], off
	v_lshl_add_u64 v[6:7], v[6:7], 0, s[4:5]
	s_mov_b64 exec, s[34:35]
	v_lshl_add_u64 v[2:3], v[2:3], 0, s[8:9]
	v_cmp_ge_u64_e32 vcc, s[16:17], v[2:3]
	s_mul_i32 s20, s10, 5
	s_mul_hi_u32 s21, s10, 5
	s_mul_i32 s22, s11, 5
	s_add_u32 s21, s21, s22
	v_lshl_add_u64 v[4:5], v[4:5], 0, s[20:21]
	s_and_b64 exec, exec, vcc
	s_cbranch_execz .LBB0_188
